# attention: one static s_setprio 1 for waves 4-7 at item start (desynchronises the two waves of each SIMD)
# speedup vs baseline: 1.0575x; 1.0023x over previous
.LBB0_485:
	s_or_b64 exec, exec, s[12:13]
	v_lshrrev_b32_e32 v8, 3, v165
	v_and_b32_e32 v8, 2, v8
	v_bfe_u32 v9, v165, 1, 1
	v_bfe_u32 v7, v165, 2, 2
	v_or_b32_e32 v10, v8, v9
	v_lshlrev_b32_e32 v166, 2, v4
	v_lshlrev_b32_e32 v11, 3, v165
	v_and_b32_e32 v11, 8, v11
	v_or_b32_e32 v13, v166, v7
	v_bitop3_b32 v8, v8, v4, v9 bitop3:0x36
	v_bitop3_b32 v10, v4, v10, 2 bitop3:0x36
	v_lshlrev_b32_e32 v3, 2, v165
	v_lshlrev_b32_e32 v12, 6, v7
	v_lshlrev_b32_e32 v13, 8, v13
	v_lshlrev_b32_e32 v8, 4, v8
	v_lshl_or_b32 v10, v10, 4, v11
	s_waitcnt vmcnt(0)
	v_or3_b32 v8, v13, v8, v11
	v_xor_b32_e32 v9, 64, v12
	v_xor_b32_e32 v14, 0x80, v12
	v_xor_b32_e32 v15, 0xc0, v12
	v_or3_b32 v10, v13, v10, s73
	v_and_b32_e32 v3, 12, v3
	v_and_b32_e32 v167, 31, v165
	v_or_b32_e32 v155, v8, v12
	v_or_b32_e32 v168, v8, v9
	v_or_b32_e32 v169, v8, v14
	v_or_b32_e32 v170, v8, v15
	v_or_b32_e32 v8, 2, v4
	v_add_u32_e32 v172, v10, v9
	v_or_b32_e32 v9, v3, v7
	v_bitop3_b32 v3, v3, v4, v7 bitop3:0x36
	v_lshlrev_b32_e32 v184, 8, v167
	v_add_u32_e32 v171, v10, v12
	v_add_u32_e32 v173, v10, v14
	v_add_u32_e32 v174, v10, v15
	v_lshlrev_b32_e32 v176, 6, v167
	v_lshlrev_b32_e32 v189, 4, v3
	s_cmp_eq_u32 s15, 1
	v_xor_b32_e32 v188, v8, v9
	v_bitop3_b32 v187, v4, v9, 4 bitop3:0x36
	v_bitop3_b32 v186, v4, v9, 6 bitop3:0x36
	v_bitop3_b32 v185, v4, v9, 8 bitop3:0x36
	v_bitop3_b32 v182, v4, v9, 10 bitop3:0x36
	v_bitop3_b32 v180, v4, v9, 12 bitop3:0x36
	v_bitop3_b32 v179, v4, v9, 14 bitop3:0x36
	v_xor_b32_e32 v178, v4, v7
	v_xor_b32_e32 v177, v8, v7
	s_waitcnt vmcnt(0) lgkmcnt(0)
	s_barrier
	v_add_u32_e32 v190, v184, v189
	v_lshl_add_u32 v191, v188, 4, v184
	v_lshl_add_u32 v192, v187, 4, v184
	v_lshl_add_u32 v193, v186, 4, v184
	v_lshl_add_u32 v194, v185, 4, v184
	v_lshl_add_u32 v195, v182, 4, v184
	v_lshl_add_u32 v196, v180, 4, v184
	v_lshl_add_u32 v198, v179, 4, v184
	v_lshl_add_u32 v199, v178, 4, v176
	v_lshl_add_u32 v200, v177, 4, v176
	v_readfirstlane_b32 s16, v181
	s_add_i32 s12, s15, -1
	s_lshr_b32 s11, s16, 12
	s_cmp_eq_u32 s11, 0
	s_cbranch_scc1 .Lat3_noprio
	s_setprio 1
.Lat3_noprio:
	s_cmp_lg_u64 s[8:9], 0
	s_cselect_b32 s17, 16, 0xffff
	s_mov_b32 s13, 0
	v_lshl_add_u64 v[162:163], v[156:157], 0, s[60:61]
	v_lshl_add_u64 v[160:161], v[158:159], 0, s[58:59]
	s_cmp_eq_u32 s15, 1
	s_cbranch_scc1 .Lat3_onetile
	s_add_u32 m0, s16, 20480
	v_lshl_add_u64 v[202:203], v[162:163], 0, s[54:55]
	global_load_lds_dwordx4 v[162:163], off
	v_lshl_add_u64 v[162:163], v[162:163], 0, s[60:61]
	s_add_u32 m0, s16, 28672
	s_nop 0
	global_load_lds_dwordx4 v[202:203], off
	s_cmp_eq_u64 s[6:7], 0
	s_cbranch_scc1 .Lat3_norope_pre
	s_add_u32 m0, s16, 36864
	s_nop 0
	global_load_lds_dwordx4 v[160:161], off
	v_lshl_add_u64 v[160:161], v[160:161], 0, s[60:61]
